# LN1 second pass: gamma/beta loads of a row hoisted ahead of the variance reduction, copied into place with counted waits (no per-group vmcnt(0))
# speedup vs baseline: 1.0163x; 1.0086x over previous
.LBB0_1578:
	s_or_b64 exec, exec, s[24:25]
	v_pk_add_f32 v[10:11], v[108:109], v[24:25]
	v_pk_add_f32 v[22:23], v[106:107], v[26:27]
	s_waitcnt vmcnt(2)
	v_add_f32_e32 v13, v16, v17
	v_pk_add_f32 v[10:11], v[10:11], v[22:23]
	v_add_f32_e32 v105, v18, v19
	v_add_f32_e32 v11, 0, v11
	v_add_f32_e32 v103, v10, v11
	v_pk_add_f32 v[10:11], v[110:111], v[20:21]
	v_pk_add_f32 v[22:23], v[12:13], v[104:105]
	v_pk_add_f32 v[10:11], v[10:11], v[10:11] op_sel_hi:[0,1]
	v_mov_b32_e32 v15, v11
	v_pk_add_f32 v[10:11], v[14:15], v[102:103]
	s_waitcnt vmcnt(1)
	v_add_f32_e32 v29, v4, v5
	v_pk_add_f32 v[10:11], v[22:23], v[10:11]
	v_pk_add_f32 v[22:23], v[100:101], v[8:9]
	v_pk_add_f32 v[10:11], v[10:11], v[10:11] op_sel_hi:[0,1]
	v_pk_add_f32 v[22:23], v[22:23], v[22:23] op_sel_hi:[0,1]
	v_add_f32_e32 v31, v6, v7
	s_waitcnt vmcnt(0)
	v_mov_b32_e32 v28, v0
	v_mov_b32_e32 v30, v1
	v_mov_b32_e32 v22, v2
	v_mov_b32_e32 v10, v3
	v_pk_add_f32 v[28:29], v[28:29], v[30:31]
	v_pk_add_f32 v[10:11], v[22:23], v[10:11]
	v_xor_b32_e32 v13, 1, v39
	v_pk_add_f32 v[10:11], v[28:29], v[10:11]
	s_nop 0
	v_add_f32_e32 v10, v10, v11
	v_and_b32_e32 v11, 64, v39
	v_add_u32_e32 v11, 64, v11
	v_cmp_lt_i32_e32 vcc, v13, v11
	s_nop 1
	v_cndmask_b32_e32 v13, v39, v13, vcc
	v_lshlrev_b32_e32 v13, 2, v13
	ds_bpermute_b32 v15, v13, v10
	s_waitcnt lgkmcnt(0)
	v_add_f32_e32 v10, v10, v15
	v_xor_b32_e32 v15, 2, v39
	v_cmp_lt_i32_e32 vcc, v15, v11
	s_nop 1
	v_cndmask_b32_e32 v15, v39, v15, vcc
	v_lshlrev_b32_e32 v15, 2, v15
	ds_bpermute_b32 v22, v15, v10
	s_waitcnt lgkmcnt(0)
	v_add_f32_e32 v10, v10, v22
	v_xor_b32_e32 v22, 4, v39
	v_cmp_lt_i32_e32 vcc, v22, v11
	s_nop 1
	v_cndmask_b32_e32 v22, v39, v22, vcc
	v_lshlrev_b32_e32 v41, 2, v22
	ds_bpermute_b32 v22, v41, v10
	s_waitcnt lgkmcnt(0)
	v_add_f32_e32 v10, v10, v22
	v_xor_b32_e32 v22, 8, v39
	v_cmp_lt_i32_e32 vcc, v22, v11
	s_nop 1
	v_cndmask_b32_e32 v22, v39, v22, vcc
	v_lshlrev_b32_e32 v43, 2, v22
	ds_bpermute_b32 v22, v43, v10
	s_waitcnt lgkmcnt(0)
	v_add_f32_e32 v10, v10, v22
	v_xor_b32_e32 v22, 16, v39
	v_cmp_lt_i32_e32 vcc, v22, v11
	s_nop 1
	v_cndmask_b32_e32 v22, v39, v22, vcc
	v_lshlrev_b32_e32 v67, 2, v22
	ds_bpermute_b32 v22, v67, v10
	s_waitcnt lgkmcnt(0)
	v_add_f32_e32 v10, v10, v22
	v_xor_b32_e32 v22, 32, v39
	v_cmp_lt_i32_e32 vcc, v22, v11
	s_nop 1
	v_cndmask_b32_e32 v11, v39, v22, vcc
	v_lshlrev_b32_e32 v69, 2, v11
	ds_bpermute_b32 v11, v69, v10
	s_waitcnt lgkmcnt(0)
	v_add_f32_e32 v71, v10, v11
	v_fmac_f32_e32 v25, 0xba000000, v71
	v_fmac_f32_e32 v24, 0xba000000, v71
	v_fmac_f32_e32 v27, 0xba000000, v71
	v_fmac_f32_e32 v109, 0xba000000, v71
	v_fmac_f32_e32 v26, 0xba000000, v71
	v_fmac_f32_e32 v108, 0xba000000, v71
	v_mov_b32_e32 v22, v25
	v_mov_b32_e32 v23, v24
	v_fmac_f32_e32 v107, 0xba000000, v71
	v_fmac_f32_e32 v106, 0xba000000, v71
	v_mov_b32_e32 v10, v109
	v_mov_b32_e32 v11, v108
	v_pk_mul_f32 v[22:23], v[22:23], v[22:23]
	v_mov_b32_e32 v28, v27
	v_mov_b32_e32 v29, v26
	v_pk_fma_f32 v[10:11], v[10:11], v[10:11], v[22:23]
	v_mov_b32_e32 v22, v107
	v_mov_b32_e32 v23, v106
	v_pk_mul_f32 v[28:29], v[28:29], v[28:29]
	v_fmac_f32_e32 v21, 0xba000000, v71
	v_pk_fma_f32 v[22:23], v[22:23], v[22:23], v[28:29]
	v_fmac_f32_e32 v111, 0xba000000, v71
	v_fmac_f32_e32 v110, 0xba000000, v71
	v_fmac_f32_e32 v20, 0xba000000, v71
	v_pk_add_f32 v[10:11], v[10:11], v[22:23]
	v_mov_b32_e32 v22, v111
	v_mov_b32_e32 v23, v21
	v_mov_b32_e32 v28, v20
	v_mov_b32_e32 v29, v110
	v_pk_add_f32 v[10:11], v[10:11], v[10:11] op_sel_hi:[0,1]
	v_pk_mul_f32 v[22:23], v[22:23], v[22:23]
	v_pk_mul_f32 v[28:29], v[28:29], v[28:29]
	v_fmac_f32_e32 v16, 0xba000000, v71
	v_pk_mov_b32 v[30:31], v[28:29], v[22:23] op_sel:[1,0]
	v_mov_b32_e32 v29, v23
	v_fmac_f32_e32 v18, 0xba000000, v71
	v_fmac_f32_e32 v17, 0xba000000, v71
	v_mul_f32_e32 v10, v16, v16
	v_pk_add_f32 v[22:23], v[30:31], v[28:29]
	v_fmac_f32_e32 v19, 0xba000000, v71
	v_pk_fma_f32 v[28:29], v[16:17], v[16:17], v[10:11] op_sel_hi:[1,1,0]
	v_mul_f32_e32 v10, v18, v18
	v_pk_add_f32 v[22:23], v[22:23], v[22:23] op_sel_hi:[0,1]
	v_pk_fma_f32 v[30:31], v[18:19], v[18:19], v[10:11] op_sel_hi:[1,1,0]
	v_fmac_f32_e32 v102, 0xba000000, v71
	v_fmac_f32_e32 v14, 0xba000000, v71
	v_fmac_f32_e32 v104, 0xba000000, v71
	v_fmac_f32_e32 v12, 0xba000000, v71
	v_mul_f32_e32 v28, v12, v12
	v_mul_f32_e32 v30, v104, v104
	v_mul_f32_e32 v22, v14, v14
	v_mul_f32_e32 v10, v102, v102
	v_pk_add_f32 v[28:29], v[28:29], v[30:31]
	v_pk_add_f32 v[10:11], v[22:23], v[10:11]
	v_fmac_f32_e32 v9, 0xba000000, v71
	v_pk_add_f32 v[10:11], v[28:29], v[10:11]
	global_load_dwordx4 v[28:31], v[44:45], off
	global_load_dwordx4 v[118:121], v[46:47], off
	global_load_dwordx4 v[128:131], v[44:45], off offset:1024
	global_load_dwordx4 v[132:135], v[46:47], off offset:1024
	global_load_dwordx4 v[136:139], v[44:45], off offset:2048
	global_load_dwordx4 v[140:143], v[46:47], off offset:2048
	global_load_dwordx4 v[144:147], v[44:45], off offset:3072
	global_load_dwordx4 v[148:151], v[46:47], off offset:3072
	global_load_dwordx4 v[152:155], v[48:49], off
	global_load_dwordx4 v[156:159], v[50:51], off
	global_load_dwordx4 v[160:163], v[52:53], off
	global_load_dwordx4 v[168:171], v[54:55], off
	global_load_dwordx4 v[172:175], v[56:57], off
	global_load_dwordx4 v[176:179], v[58:59], off
	global_load_dwordx4 v[180:183], v[60:61], off
	global_load_dwordx4 v[184:187], v[62:63], off
	v_fmac_f32_e32 v101, 0xba000000, v71
	v_fmac_f32_e32 v100, 0xba000000, v71
	v_fmac_f32_e32 v8, 0xba000000, v71
	v_mov_b32_e32 v22, v101
	v_mov_b32_e32 v23, v9
	v_mov_b32_e32 v112, v8
	v_mov_b32_e32 v113, v100
	v_fmac_f32_e32 v4, 0xba000000, v71
	v_pk_mul_f32 v[22:23], v[22:23], v[22:23]
	v_pk_mul_f32 v[112:113], v[112:113], v[112:113]
	v_fmamk_f32 v116, v71, 0xba000000, v6
	v_fmamk_f32 v5, v71, 0xba000000, v5
	v_mul_f32_e32 v6, v4, v4
	v_pk_mov_b32 v[114:115], v[112:113], v[22:23] op_sel:[1,0]
	v_mov_b32_e32 v113, v23
	v_fmamk_f32 v117, v71, 0xba000000, v7
	v_pk_fma_f32 v[6:7], v[4:5], v[4:5], v[6:7] op_sel_hi:[1,1,0]
	v_pk_add_f32 v[22:23], v[114:115], v[112:113]
	v_mul_f32_e32 v6, v116, v116
	v_pk_add_f32 v[10:11], v[10:11], v[10:11] op_sel_hi:[0,1]
	v_pk_add_f32 v[22:23], v[22:23], v[22:23] op_sel_hi:[0,1]
	v_pk_fma_f32 v[114:115], v[116:117], v[116:117], v[6:7] op_sel_hi:[1,1,0]
	v_fmamk_f32 v113, v71, 0xba000000, v3
	v_fmamk_f32 v112, v71, 0xba000000, v2
	v_fmamk_f32 v1, v71, 0xba000000, v1
	v_fmac_f32_e32 v0, 0xba000000, v71
	v_mul_f32_e32 v6, v0, v0
	v_mul_f32_e32 v114, v1, v1
	v_mul_f32_e32 v22, v112, v112
	v_mul_f32_e32 v10, v113, v113
	v_pk_add_f32 v[2:3], v[6:7], v[114:115]
	v_pk_add_f32 v[6:7], v[22:23], v[10:11]
	s_nop 0
	v_pk_add_f32 v[2:3], v[2:3], v[6:7]
	v_mov_b32_e32 v7, v27
	v_add_f32_e32 v2, v2, v3
	ds_bpermute_b32 v3, v13, v2
	s_waitcnt lgkmcnt(0)
	v_add_f32_e32 v2, v2, v3
	ds_bpermute_b32 v3, v15, v2
	s_waitcnt lgkmcnt(0)
	v_add_f32_e32 v2, v2, v3
	ds_bpermute_b32 v3, v41, v2
	s_waitcnt lgkmcnt(0)
	v_add_f32_e32 v2, v2, v3
	ds_bpermute_b32 v3, v43, v2
	s_waitcnt lgkmcnt(0)
	v_add_f32_e32 v2, v2, v3
	ds_bpermute_b32 v3, v67, v2
	s_waitcnt lgkmcnt(0)
	v_add_f32_e32 v3, v2, v3
	ds_bpermute_b32 v6, v69, v3
	v_mov_b32_e32 v2, v109
	s_waitcnt lgkmcnt(0)
	v_add_f32_e32 v3, v3, v6
	v_fmamk_f32 v3, v3, 0x3a000000, v37
	v_mul_f32_e32 v6, 0x4b800000, v3
	v_cmp_gt_f32_e32 vcc, s28, v3
	s_nop 1
	v_cndmask_b32_e32 v3, v3, v6, vcc
	v_rsq_f32_e32 v10, v3
	v_mov_b32_e32 v3, v25
	v_mov_b32_e32 v6, v107
	v_mul_f32_e32 v11, 0x45800000, v10
	v_cndmask_b32_e32 v114, v10, v11, vcc
	v_pk_mul_f32 v[2:3], v[2:3], v[114:115] op_sel_hi:[1,0]
	v_pk_mul_f32 v[6:7], v[6:7], v[114:115] op_sel_hi:[1,0]
	v_cmp_lt_i32_e32 vcc, s27, v96
	s_waitcnt vmcnt(14)
	v_pk_fma_f32 v[30:31], v[30:31], v[6:7], v[120:121]
	v_pk_fma_f32 v[28:29], v[28:29], v[2:3], v[118:119]
	s_and_saveexec_b64 s[24:25], vcc
	s_cbranch_execz .LBB0_1580
	v_mov_b32_e32 v95, v35
	v_lshl_add_u64 v[2:3], v[98:99], 0, v[94:95]
	global_store_dwordx4 v[2:3], v[28:31], off
.LBB0_1580:
	s_or_b64 exec, exec, s[24:25]
	v_lshlrev_b64 v[2:3], 11, v[96:97]
	v_lshl_add_u64 v[96:97], v[2:3], 1, s[10:11]
	v_bfe_u32 v2, v28, 16, 1
	v_add3_u32 v2, v28, v2, s29
	v_bfe_u32 v3, v29, 16, 1
	v_lshrrev_b32_e32 v2, 16, v2
	v_add3_u32 v3, v29, v3, s29
	v_and_or_b32 v2, v3, s30, v2
	v_bfe_u32 v3, v30, 16, 1
	v_add3_u32 v3, v30, v3, s29
	v_bfe_u32 v6, v31, 16, 1
	v_lshrrev_b32_e32 v3, 16, v3
	v_add3_u32 v6, v31, v6, s29
	v_and_or_b32 v3, v6, s30, v3
	v_lshl_add_u64 v[6:7], v[96:97], 0, v[34:35]
	global_store_dwordx2 v[6:7], v[2:3], off
	s_waitcnt vmcnt(13)
	v_mov_b64_e32 v[28:29], v[128:129]
	v_mov_b64_e32 v[30:31], v[130:131]
	v_mov_b64_e32 v[118:119], v[132:133]
	v_mov_b64_e32 v[120:121], v[134:135]
	v_mov_b32_e32 v109, v24
	v_mov_b32_e32 v115, v114
	v_mov_b32_e32 v2, v114
	v_mov_b32_e32 v3, v114
	v_mov_b32_e32 v107, v26
	v_pk_mul_f32 v[6:7], v[106:107], v[2:3]
	v_pk_mul_f32 v[10:11], v[108:109], v[114:115]
	s_waitcnt vmcnt(13)
	v_pk_fma_f32 v[24:25], v[6:7], v[30:31], v[120:121]
	v_pk_fma_f32 v[22:23], v[10:11], v[28:29], v[118:119]
	s_and_saveexec_b64 s[24:25], vcc
	s_cbranch_execz .LBB0_1582
	v_mov_b32_e32 v95, v35
	v_lshl_add_u64 v[6:7], v[98:99], 0, v[94:95]
	global_store_dwordx4 v[6:7], v[22:25], off offset:1024
.LBB0_1582:
	s_or_b64 exec, exec, s[24:25]
	v_bfe_u32 v6, v22, 16, 1
	v_add3_u32 v6, v22, v6, s29
	v_bfe_u32 v7, v23, 16, 1
	v_lshrrev_b32_e32 v6, 16, v6
	v_add3_u32 v7, v23, v7, s29
	v_and_or_b32 v6, v7, s30, v6
	v_bfe_u32 v7, v24, 16, 1
	v_add3_u32 v7, v24, v7, s29
	v_bfe_u32 v10, v25, 16, 1
	v_lshrrev_b32_e32 v7, 16, v7
	v_add3_u32 v10, v25, v10, s29
	v_mov_b32_e32 v73, v35
	v_and_or_b32 v7, v10, s30, v7
	v_lshl_add_u64 v[10:11], v[96:97], 0, v[72:73]
	global_store_dwordx2 v[10:11], v[6:7], off
	s_waitcnt vmcnt(12)
	v_mov_b64_e32 v[24:25], v[136:137]
	v_mov_b64_e32 v[26:27], v[138:139]
	v_mov_b64_e32 v[28:29], v[140:141]
	v_mov_b64_e32 v[30:31], v[142:143]
	v_mov_b32_e32 v6, v20
	v_mov_b32_e32 v7, v110
	v_mov_b32_e32 v20, v111
	v_pk_mul_f32 v[2:3], v[20:21], v[2:3]
	v_pk_mul_f32 v[6:7], v[6:7], v[114:115]
	s_waitcnt vmcnt(12)
	v_pk_fma_f32 v[22:23], v[2:3], v[26:27], v[30:31]
	v_pk_fma_f32 v[20:21], v[6:7], v[24:25], v[28:29]
	s_and_saveexec_b64 s[24:25], vcc
	s_cbranch_execz .LBB0_1584
	v_mov_b32_e32 v95, v35
	v_lshl_add_u64 v[2:3], v[98:99], 0, v[94:95]
	global_store_dwordx4 v[2:3], v[20:23], off offset:2048
.LBB0_1584:
	s_or_b64 exec, exec, s[24:25]
	v_bfe_u32 v2, v20, 16, 1
	v_add3_u32 v2, v20, v2, s29
	v_bfe_u32 v3, v21, 16, 1
	v_lshrrev_b32_e32 v2, 16, v2
	v_add3_u32 v3, v21, v3, s29
	v_and_or_b32 v2, v3, s30, v2
	v_bfe_u32 v3, v22, 16, 1
	v_add3_u32 v3, v22, v3, s29
	v_bfe_u32 v6, v23, 16, 1
	v_lshrrev_b32_e32 v3, 16, v3
	v_add3_u32 v6, v23, v6, s29
	v_mov_b32_e32 v75, v35
	v_and_or_b32 v3, v6, s30, v3
	v_lshl_add_u64 v[6:7], v[96:97], 0, v[74:75]
	global_store_dwordx2 v[6:7], v[2:3], off
	s_waitcnt vmcnt(11)
	v_mov_b64_e32 v[20:21], v[144:145]
	v_mov_b64_e32 v[22:23], v[146:147]
	v_mov_b64_e32 v[24:25], v[148:149]
	v_mov_b64_e32 v[26:27], v[150:151]
	v_mov_b32_e32 v2, v114
	v_mov_b32_e32 v3, v114
	v_pk_mul_f32 v[6:7], v[16:17], v[114:115]
	v_pk_mul_f32 v[10:11], v[18:19], v[2:3]
	s_waitcnt vmcnt(11)
	v_pk_fma_f32 v[16:17], v[6:7], v[20:21], v[24:25]
	v_pk_fma_f32 v[18:19], v[10:11], v[22:23], v[26:27]
	s_and_saveexec_b64 s[24:25], vcc
	s_cbranch_execz .LBB0_1586
	v_mov_b32_e32 v95, v35
	v_lshl_add_u64 v[6:7], v[98:99], 0, v[94:95]
	global_store_dwordx4 v[6:7], v[16:19], off offset:3072
.LBB0_1586:
	s_or_b64 exec, exec, s[24:25]
	v_bfe_u32 v6, v16, 16, 1
	v_add3_u32 v6, v16, v6, s29
	v_bfe_u32 v7, v17, 16, 1
	v_lshrrev_b32_e32 v6, 16, v6
	v_add3_u32 v7, v17, v7, s29
	v_and_or_b32 v6, v7, s30, v6
	v_bfe_u32 v7, v18, 16, 1
	v_add3_u32 v7, v18, v7, s29
	v_bfe_u32 v10, v19, 16, 1
	v_lshrrev_b32_e32 v7, 16, v7
	v_add3_u32 v10, v19, v10, s29
	v_mov_b32_e32 v77, v35
	v_and_or_b32 v7, v10, s30, v7
	v_lshl_add_u64 v[10:11], v[96:97], 0, v[76:77]
	global_store_dwordx2 v[10:11], v[6:7], off
	s_waitcnt vmcnt(10)
	v_mov_b64_e32 v[16:17], v[152:153]
	v_mov_b64_e32 v[18:19], v[154:155]
	v_mov_b64_e32 v[20:21], v[156:157]
	v_mov_b64_e32 v[22:23], v[158:159]
	v_mov_b32_e32 v13, v104
	v_mov_b32_e32 v15, v102
	v_pk_mul_f32 v[2:3], v[14:15], v[2:3]
	v_pk_mul_f32 v[6:7], v[12:13], v[114:115]
	s_waitcnt vmcnt(10)
	v_pk_fma_f32 v[12:13], v[2:3], v[18:19], v[22:23]
	v_pk_fma_f32 v[10:11], v[6:7], v[16:17], v[20:21]
	s_and_saveexec_b64 s[24:25], vcc
	s_cbranch_execz .LBB0_1588
	v_mov_b32_e32 v93, v35
	v_lshl_add_u64 v[2:3], v[98:99], 0, v[92:93]
	global_store_dwordx4 v[2:3], v[10:13], off
.LBB0_1588:
	s_or_b64 exec, exec, s[24:25]
	v_bfe_u32 v2, v10, 16, 1
	v_add3_u32 v2, v10, v2, s29
	v_bfe_u32 v3, v11, 16, 1
	v_lshrrev_b32_e32 v2, 16, v2
	v_add3_u32 v3, v11, v3, s29
	v_and_or_b32 v2, v3, s30, v2
	v_bfe_u32 v3, v12, 16, 1
	v_add3_u32 v3, v12, v3, s29
	v_bfe_u32 v6, v13, 16, 1
	v_lshrrev_b32_e32 v3, 16, v3
	v_add3_u32 v6, v13, v6, s29
	v_mov_b32_e32 v79, v35
	v_and_or_b32 v3, v6, s30, v3
	v_lshl_add_u64 v[6:7], v[96:97], 0, v[78:79]
	global_store_dwordx2 v[6:7], v[2:3], off
	s_waitcnt vmcnt(9)
	v_mov_b64_e32 v[10:11], v[160:161]
	v_mov_b64_e32 v[12:13], v[162:163]
	v_mov_b64_e32 v[14:15], v[168:169]
	v_mov_b64_e32 v[16:17], v[170:171]
	v_mov_b32_e32 v6, v8
	v_mov_b32_e32 v7, v100
	v_mov_b32_e32 v2, v114
	v_mov_b32_e32 v3, v114
	v_mov_b32_e32 v8, v101
	v_pk_mul_f32 v[8:9], v[8:9], v[2:3]
	v_pk_mul_f32 v[6:7], v[6:7], v[114:115]
	s_waitcnt vmcnt(9)
	v_pk_fma_f32 v[8:9], v[8:9], v[12:13], v[16:17]
	v_pk_fma_f32 v[6:7], v[6:7], v[10:11], v[14:15]
	s_and_saveexec_b64 s[24:25], vcc
	s_cbranch_execz .LBB0_1590
	v_mov_b32_e32 v91, v35
	v_lshl_add_u64 v[10:11], v[98:99], 0, v[90:91]
	global_store_dwordx4 v[10:11], v[6:9], off
.LBB0_1590:
	s_or_b64 exec, exec, s[24:25]
	v_bfe_u32 v10, v6, 16, 1
	v_add3_u32 v6, v6, v10, s29
	v_bfe_u32 v10, v7, 16, 1
	v_lshrrev_b32_e32 v6, 16, v6
	v_add3_u32 v7, v7, v10, s29
	v_and_or_b32 v6, v7, s30, v6
	v_bfe_u32 v7, v8, 16, 1
	v_add3_u32 v7, v8, v7, s29
	v_bfe_u32 v8, v9, 16, 1
	v_lshrrev_b32_e32 v7, 16, v7
	v_add3_u32 v8, v9, v8, s29
	v_mov_b32_e32 v81, v35
	v_and_or_b32 v7, v8, s30, v7
	v_lshl_add_u64 v[8:9], v[96:97], 0, v[80:81]
	global_store_dwordx2 v[8:9], v[6:7], off
	s_waitcnt vmcnt(8)
	v_mov_b64_e32 v[6:7], v[172:173]
	v_mov_b64_e32 v[8:9], v[174:175]
	s_nop 0
	v_mov_b64_e32 v[10:11], v[176:177]
	v_mov_b64_e32 v[12:13], v[178:179]
	v_pk_mul_f32 v[2:3], v[116:117], v[2:3]
	v_pk_mul_f32 v[14:15], v[4:5], v[114:115]
	s_waitcnt vmcnt(8)
	v_pk_fma_f32 v[4:5], v[2:3], v[8:9], v[12:13]
	v_pk_fma_f32 v[2:3], v[14:15], v[6:7], v[10:11]
	s_and_saveexec_b64 s[24:25], vcc
	s_cbranch_execz .LBB0_1592
	v_mov_b32_e32 v89, v35
	v_lshl_add_u64 v[6:7], v[98:99], 0, v[88:89]
	global_store_dwordx4 v[6:7], v[2:5], off
.LBB0_1592:
	s_or_b64 exec, exec, s[24:25]
	v_bfe_u32 v6, v2, 16, 1
	v_add3_u32 v2, v2, v6, s29
	v_bfe_u32 v6, v3, 16, 1
	v_lshrrev_b32_e32 v2, 16, v2
	v_add3_u32 v3, v3, v6, s29
	v_and_or_b32 v2, v3, s30, v2
	v_bfe_u32 v3, v4, 16, 1
	v_add3_u32 v3, v4, v3, s29
	v_bfe_u32 v4, v5, 16, 1
	v_lshrrev_b32_e32 v3, 16, v3
	v_add3_u32 v4, v5, v4, s29
	v_mov_b32_e32 v83, v35
	v_and_or_b32 v3, v4, s30, v3
	v_lshl_add_u64 v[4:5], v[96:97], 0, v[82:83]
	global_store_dwordx2 v[4:5], v[2:3], off
	s_waitcnt vmcnt(7)
	v_mov_b64_e32 v[4:5], v[180:181]
	v_mov_b64_e32 v[6:7], v[182:183]
	s_nop 0
	v_mov_b64_e32 v[8:9], v[184:185]
	v_mov_b64_e32 v[10:11], v[186:187]
	v_mov_b32_e32 v2, v114
	v_mov_b32_e32 v3, v114
	v_pk_mul_f32 v[0:1], v[0:1], v[114:115]
	v_pk_mul_f32 v[2:3], v[112:113], v[2:3]
	s_waitcnt vmcnt(7)
	v_pk_fma_f32 v[0:1], v[0:1], v[4:5], v[8:9]
	v_pk_fma_f32 v[2:3], v[2:3], v[6:7], v[10:11]
	s_and_saveexec_b64 s[24:25], vcc
	s_cbranch_execz .LBB0_1594
	v_mov_b32_e32 v87, v35
	v_lshl_add_u64 v[4:5], v[98:99], 0, v[86:87]
	global_store_dwordx4 v[4:5], v[0:3], off
